# GLA3 tail: r/gnorm loads hoisted, no per-chunk vmcnt(0); pool item: 5 token-chunk + 8 weight-row + 4 scale loads issued together (were 21 serialized load-wait pairs)
# speedup vs baseline: 1.0044x; 1.0039x over previous
; DI unsigned pk_bf16(float lo, float hi) { unsigned r; asm("v_cvt_pk_bf16_f32 %0, %1, %2" : "=v"(r) : "v"(lo), "v"(hi)); return r; }
; DI float lo_f(unsigned w) { return __uint_as_float(w << 16); }
; DI float hi_f(unsigned w) { return __uint_as_float(w & 0xffff0000u); }
; DI float siluf_(float x) { return x * __builtin_amdgcn_rcpf(1.f + __expf(-x)); }
; DI float shx(float v, int m, int lane) { return __int_as_float(__builtin_amdgcn_ds_bpermute((lane ^ m) << 2, __float_as_int(v))); }
; DI void gla_pass3_item(unsigned char* ws, const float* wa2, const float* gba, const float* gnorm, unsigned char* lds, int cid, int hh) {
;     ...
;     if (dir == 0) {
;         float ss = 0.f;
; #pragma unroll
;         for (int nt = 0; nt < 4; ++nt) {
;             const float* ob = OB + (mt * 16 + fr) * 66 + nt * 16 + fq * 4;
;             const f32x2 b0 = *(const f32x2*)ob, b1 = *(const f32x2*)(ob + 2);
;             o4[nt][0] += b0[0]; o4[nt][1] += b0[1]; o4[nt][2] += b1[0]; o4[nt][3] += b1[1];
;             ss += o4[nt][0] * o4[nt][0] + o4[nt][1] * o4[nt][1] + o4[nt][2] * o4[nt][2] + o4[nt][3] * o4[nt][3];
;         }
;         ss += shx(ss, 16, lane); ss += shx(ss, 32, lane);
;         float eps = EPS; asm volatile("" : "+v"(eps));
;         const float rs = rsqrtf(ss * (1.f / 64.f) + eps);
;         const size_t row = (size_t)cid * 64 + mt * 16 + fr;
; #pragma unroll
;         for (int nt = 0; nt < 4; ++nt) {
;             const int e = nt * 16 + fq * 4;
;             const f32x4 gn = *(const f32x4*)(gnorm + hh * 64 + e);
;             const u32x2 rv = *(const u32x2*)(P + row * IN_DIM + C_GR + hh * 64 + e);
;             const float r0 = lo_f(rv[0]), r1 = hi_f(rv[0]), r2 = lo_f(rv[1]), r3 = hi_f(rv[1]);
;             u32x2 ov; ov[0] = pk_bf16(o4[nt][0] * rs * gn[0] * siluf_(r0), o4[nt][1] * rs * gn[1] * siluf_(r1)); ov[1] = pk_bf16(o4[nt][2] * rs * gn[2] * siluf_(r2), o4[nt][3] * rs * gn[3] * siluf_(r3));
.LBB0_131:
	s_or_b64 exec, exec, s[20:21]
	s_waitcnt lgkmcnt(0)
	s_barrier
	s_and_saveexec_b64 s[40:41], vcc
	s_cbranch_execz .LBB0_128
	s_add_u32 s2, s42, s12
	s_addc_u32 s6, s43, s13
	s_lshl_b32 s7, s72, 2
	ds_read2_b64 v[22:25], v18 offset1:1
	ds_read2_b64 v[26:29], v18 offset0:8 offset1:9
	ds_read2_b64 v[30:33], v18 offset0:16 offset1:17
	ds_read2_b64 v[34:37], v18 offset0:24 offset1:25
	v_or_b32_e32 v42, s16, v0
	s_add_u32 s42, s2, s7
	v_mov_b64_e32 v[18:19], s[76:77]
	s_addc_u32 s43, s6, 0
	v_mad_u64_u32 v[18:19], s[6:7], v42, s28, v[18:19]
	v_mov_b32_e32 v0, 0x2640
	v_mad_i32_i24 v19, s17, v0, v19
	s_lshl_b32 s72, s72, 1
	v_lshl_add_u64 v[18:19], v[18:19], 0, s[72:73]
	v_lshlrev_b32_e32 v0, 1, v21
	v_mov_b32_e32 v48, 0x358637bd
	v_lshl_add_u64 v[18:19], v[18:19], 0, v[0:1]
	global_load_dwordx2 v[44:45], v[18:19], off offset:3072
	global_load_dwordx2 v[50:51], v[18:19], off offset:3104
	global_load_dwordx2 v[52:53], v[18:19], off offset:3136
	global_load_dwordx2 v[54:55], v[18:19], off offset:3168
	v_lshlrev_b32_e32 v49, 2, v21
	global_load_dwordx4 v[38:41], v49, s[42:43]
	global_load_dwordx4 v[64:67], v49, s[42:43] offset:64
	global_load_dwordx4 v[68:71], v49, s[42:43] offset:128
	global_load_dwordx4 v[72:75], v49, s[42:43] offset:192
	v_mov_b32_e32 v21, v10
	s_waitcnt lgkmcnt(0)
	v_mov_b32_e32 v47, v26
	v_mov_b32_e32 v10, v7
	v_mov_b32_e32 v26, v23
	v_and_b32_e32 v43, 63, v20
	v_mov_b32_e32 v20, v6
	v_mov_b32_e32 v46, v22
	v_pk_add_f32 v[22:23], v[10:11], v[26:27]
	v_mov_b32_e32 v6, v8
	v_mov_b32_e32 v7, v12
	v_mov_b32_e32 v10, v24
	v_mov_b32_e32 v11, v28
	v_pk_add_f32 v[20:21], v[20:21], v[46:47]
	v_pk_add_f32 v[26:27], v[6:7], v[10:11]
	v_pk_mul_f32 v[6:7], v[22:23], v[22:23]
	v_mov_b32_e32 v12, v9
	v_mov_b32_e32 v28, v25
	v_pk_fma_f32 v[6:7], v[20:21], v[20:21], v[6:7]
	v_pk_add_f32 v[24:25], v[12:13], v[28:29]
	v_pk_fma_f32 v[6:7], v[26:27], v[26:27], v[6:7]
	v_mov_b32_e32 v8, v30
	v_pk_fma_f32 v[12:13], v[24:25], v[24:25], v[6:7]
	v_mov_b32_e32 v6, v2
	v_mov_b32_e32 v7, v14
	v_mov_b32_e32 v9, v34
	v_mov_b32_e32 v14, v3
	v_mov_b32_e32 v34, v31
	v_pk_add_f32 v[10:11], v[6:7], v[8:9]
	v_pk_add_f32 v[8:9], v[14:15], v[34:35]
	v_mov_b32_e32 v2, v4
	v_mov_b32_e32 v3, v16
	v_mov_b32_e32 v6, v32
	v_mov_b32_e32 v7, v36
	v_mov_b32_e32 v16, v5
	v_pk_mul_f32 v[4:5], v[8:9], v[8:9]
	v_pk_add_f32 v[6:7], v[2:3], v[6:7]
	v_mov_b32_e32 v36, v33
	v_pk_fma_f32 v[4:5], v[10:11], v[10:11], v[4:5]
	v_pk_add_f32 v[2:3], v[16:17], v[36:37]
	v_pk_fma_f32 v[4:5], v[6:7], v[6:7], v[4:5]
	v_add_f32_e32 v12, v12, v13
	v_pk_fma_f32 v[4:5], v[2:3], v[2:3], v[4:5]
	v_add_f32_e32 v4, v12, v4
	v_add_f32_e32 v4, v4, v5
	v_lshlrev_b32_e32 v5, 2, v43
	v_xor_b32_e32 v12, 64, v5
	ds_bpermute_b32 v12, v12, v4
	v_mov_b32_e32 v43, s17
	s_mov_b64 s[6:7], 0x28e2600
	s_waitcnt lgkmcnt(0)
	v_add_f32_e32 v12, v4, v12
	v_xor_b32_e32 v4, 0x80, v5
	ds_bpermute_b32 v13, v4, v12
	v_lshlrev_b64 v[4:5], 11, v[42:43]
	v_lshl_add_u64 v[4:5], s[84:85], 0, v[4:5]
	v_lshl_add_u64 v[4:5], v[4:5], 0, s[72:73]
	v_lshl_add_u64 v[4:5], v[4:5], 0, v[0:1]
	s_waitcnt lgkmcnt(0)
	v_add_f32_e32 v12, v12, v13
	v_fmac_f32_e32 v48, 0x3c800000, v12
	v_mul_f32_e32 v12, 0x4b800000, v48
	v_cmp_gt_f32_e32 vcc, s60, v48
	s_waitcnt vmcnt(0)
; DI unsigned pk_bf16(float lo, float hi) { unsigned r; asm("v_cvt_pk_bf16_f32 %0, %1, %2" : "=v"(r) : "v"(lo), "v"(hi)); return r; }
; DI float lo_f(unsigned w) { return __uint_as_float(w << 16); }
; DI float hi_f(unsigned w) { return __uint_as_float(w & 0xffff0000u); }
; DI float siluf_(float x) { return x * __builtin_amdgcn_rcpf(1.f + __expf(-x)); }
; DI void gla_pass3_item(unsigned char* ws, const float* wa2, const float* gba, const float* gnorm, unsigned char* lds, int cid, int hh) {
;     ...
; #pragma unroll
;         for (int nt = 0; nt < 4; ++nt) {
;             const int e = nt * 16 + fq * 4;
;             const f32x4 gn = *(const f32x4*)(gnorm + hh * 64 + e);
;             const u32x2 rv = *(const u32x2*)(P + row * IN_DIM + C_GR + hh * 64 + e);
;             const float r0 = lo_f(rv[0]), r1 = hi_f(rv[0]), r2 = lo_f(rv[1]), r3 = hi_f(rv[1]);
;             u32x2 ov; ov[0] = pk_bf16(o4[nt][0] * rs * gn[0] * siluf_(r0), o4[nt][1] * rs * gn[1] * siluf_(r1)); ov[1] = pk_bf16(o4[nt][2] * rs * gn[2] * siluf_(r2), o4[nt][3] * rs * gn[3] * siluf_(r3));
;             *(u32x2*)(Y + row * 1024 + 768 + hh * 64 + e) = ov;
;         }
	v_mov_b32_e32 v16, v50
	v_mov_b32_e32 v17, v51
	v_and_b32_e32 v14, 0xffff0000, v44
	v_cndmask_b32_e32 v12, v48, v12, vcc
	v_rsq_f32_e32 v12, v12
	v_mov_b32_e32 v33, v38
	v_lshlrev_b32_e32 v28, 16, v45
	v_and_b32_e32 v30, 0xffff0000, v45
	v_mul_f32_e32 v13, 0x45800000, v12
	v_cndmask_b32_e32 v36, v12, v13, vcc
	v_lshlrev_b32_e32 v12, 16, v44
	v_mul_f32_e32 v13, 0xbfb8aa3b, v12
	v_exp_f32_e32 v15, v13
	v_mul_f32_e32 v13, v20, v36
	v_mul_f32_e32 v20, 0xbfb8aa3b, v14
	v_exp_f32_e32 v20, v20
	v_add_f32_e32 v15, 1.0, v15
	v_rcp_f32_e32 v32, v15
	v_mul_f32_e32 v29, v26, v36
	v_add_f32_e32 v15, 1.0, v20
	v_rcp_f32_e32 v38, v15
	v_pk_mul_f32 v[12:13], v[32:33], v[12:13]
	v_mul_f32_e32 v15, v22, v36
	v_mul_f32_e32 v20, v12, v13
	v_pk_mul_f32 v[12:13], v[38:39], v[14:15]
	v_mul_f32_e32 v14, 0xbfb8aa3b, v30
	v_mul_f32_e32 v12, v12, v13
	v_mul_f32_e32 v13, 0xbfb8aa3b, v28
	v_exp_f32_e32 v13, v13
	v_cvt_pk_bf16_f32 v12, v20, v12
	v_exp_f32_e32 v20, v14
	v_mov_b32_e32 v15, v40
	v_add_f32_e32 v13, 1.0, v13
	v_rcp_f32_e32 v14, v13
	v_add_f32_e32 v13, 1.0, v20
	v_rcp_f32_e32 v40, v13
	v_mul_f32_e32 v31, v24, v36
	v_pk_mul_f32 v[14:15], v[14:15], v[28:29]
	v_mul_f32_e32 v22, v23, v36
	v_mul_f32_e32 v13, v14, v15
	v_pk_mul_f32 v[14:15], v[40:41], v[30:31]
	v_mul_f32_e32 v26, v25, v36
	v_mul_f32_e32 v14, v14, v15
	v_cvt_pk_bf16_f32 v13, v13, v14
	v_add_co_u32_e32 v14, vcc, s74, v4
	v_mul_f32_e32 v20, v21, v36
	s_nop 0
	v_addc_co_u32_e32 v15, vcc, 0, v5, vcc
	global_store_dwordx2 v[14:15], v[12:13], off offset:1536
	v_and_b32_e32 v23, 0xffff0000, v16
	v_lshlrev_b32_e32 v25, 16, v17
	v_mul_f32_e32 v24, v27, v36
	v_lshlrev_b32_e32 v21, 16, v16
	v_and_b32_e32 v27, 0xffff0000, v17
	v_mul_f32_e32 v16, 0xbfb8aa3b, v23
	v_mul_f32_e32 v17, 0xbfb8aa3b, v25
	v_exp_f32_e32 v16, v16
	v_exp_f32_e32 v17, v17
	v_mul_f32_e32 v0, 0xbfb8aa3b, v21
	v_mul_f32_e32 v28, 0xbfb8aa3b, v27
	v_exp_f32_e32 v0, v0
	v_exp_f32_e32 v28, v28
	v_add_f32_e32 v30, 1.0, v16
	v_add_f32_e32 v32, 1.0, v17
	v_add_f32_e32 v0, 1.0, v0
	v_add_f32_e32 v28, 1.0, v28
	v_rcp_f32_e32 v29, v0
	v_rcp_f32_e32 v31, v30
	v_rcp_f32_e32 v33, v32
	v_rcp_f32_e32 v35, v28
	v_lshl_add_u64 v[4:5], v[4:5], 0, s[6:7]
	v_mov_b32_e32 v28, v64
	v_mov_b32_e32 v30, v65
	v_mov_b32_e32 v32, v66
	v_mov_b32_e32 v34, v67
	v_pk_mul_f32 v[12:13], v[28:29], v[20:21]
	v_pk_mul_f32 v[14:15], v[30:31], v[22:23]
	v_pk_mul_f32 v[20:21], v[32:33], v[24:25]
	v_pk_mul_f32 v[22:23], v[34:35], v[26:27]
	v_mul_f32_e32 v0, v12, v13
	v_mul_f32_e32 v12, v14, v15
	v_mul_f32_e32 v13, v20, v21
	v_mul_f32_e32 v14, v22, v23
	v_cvt_pk_bf16_f32 v12, v0, v12
	v_cvt_pk_bf16_f32 v13, v13, v14
	global_store_dwordx2 v[4:5], v[12:13], off offset:32
	v_lshlrev_b32_e32 v21, 16, v52
	v_and_b32_e32 v23, 0xffff0000, v52
	v_lshlrev_b32_e32 v25, 16, v53
	v_and_b32_e32 v27, 0xffff0000, v53
	v_mul_f32_e32 v22, v8, v36
	v_mul_f32_e32 v24, v6, v36
	v_mul_f32_e32 v26, v2, v36
	v_mul_f32_e32 v0, 0xbfb8aa3b, v21
	v_mul_f32_e32 v2, 0xbfb8aa3b, v23
	v_mul_f32_e32 v6, 0xbfb8aa3b, v25
	v_mul_f32_e32 v8, 0xbfb8aa3b, v27
	v_exp_f32_e32 v0, v0
	v_exp_f32_e32 v2, v2
	v_exp_f32_e32 v6, v6
	v_exp_f32_e32 v8, v8
	v_add_f32_e32 v0, 1.0, v0
	v_add_f32_e32 v2, 1.0, v2
	v_add_f32_e32 v6, 1.0, v6
	v_add_f32_e32 v8, 1.0, v8
	v_rcp_f32_e32 v17, v0
	v_rcp_f32_e32 v29, v2
	v_rcp_f32_e32 v31, v6
	v_rcp_f32_e32 v33, v8
	v_mul_f32_e32 v20, v10, v36
	v_mul_f32_e32 v10, v3, v36
	v_mov_b32_e32 v16, v68
	v_mov_b32_e32 v28, v69
	v_mov_b32_e32 v30, v70
	v_mov_b32_e32 v32, v71
	v_pk_mul_f32 v[12:13], v[16:17], v[20:21]
	v_pk_mul_f32 v[14:15], v[28:29], v[22:23]
	v_pk_mul_f32 v[16:17], v[30:31], v[24:25]
	v_pk_mul_f32 v[20:21], v[32:33], v[26:27]
	v_mul_f32_e32 v0, v12, v13
	v_mul_f32_e32 v2, v14, v15
	v_mul_f32_e32 v6, v16, v17
	v_mul_f32_e32 v8, v20, v21
	v_cvt_pk_bf16_f32 v12, v0, v2
	v_cvt_pk_bf16_f32 v13, v6, v8
	global_store_dwordx2 v[4:5], v[12:13], off offset:64
	v_lshlrev_b32_e32 v17, 16, v54
	v_and_b32_e32 v21, 0xffff0000, v54
	v_lshlrev_b32_e32 v23, 16, v55
	v_mul_f32_e32 v8, v7, v36
	v_and_b32_e32 v19, 0xffff0000, v55
	v_mul_f32_e32 v0, 0xbfb8aa3b, v17
	v_mul_f32_e32 v3, 0xbfb8aa3b, v21
	v_mul_f32_e32 v7, 0xbfb8aa3b, v23
	v_mul_f32_e32 v6, v9, v36
	v_mul_f32_e32 v9, 0xbfb8aa3b, v19
	v_exp_f32_e32 v0, v0
	v_exp_f32_e32 v3, v3
	v_exp_f32_e32 v7, v7
	v_exp_f32_e32 v9, v9
	v_mul_f32_e32 v2, v11, v36
	v_add_f32_e32 v0, 1.0, v0
	v_add_f32_e32 v11, 1.0, v3
	v_add_f32_e32 v16, 1.0, v7
	v_add_f32_e32 v18, 1.0, v9
	v_rcp_f32_e32 v3, v0
	v_rcp_f32_e32 v7, v11
	v_rcp_f32_e32 v9, v16
	v_rcp_f32_e32 v11, v18
	v_mov_b32_e32 v16, v72
	v_mov_b32_e32 v20, v73
	v_mov_b32_e32 v22, v74
	v_mov_b32_e32 v18, v75
	v_pk_mul_f32 v[2:3], v[2:3], v[16:17]
	v_pk_mul_f32 v[6:7], v[6:7], v[20:21]
	v_pk_mul_f32 v[8:9], v[8:9], v[22:23]
	v_pk_mul_f32 v[10:11], v[10:11], v[18:19]
	v_mul_f32_e32 v0, v2, v3
	v_mul_f32_e32 v2, v6, v7
	v_mul_f32_e32 v3, v8, v9
	v_mul_f32_e32 v6, v10, v11
	v_cvt_pk_bf16_f32 v2, v0, v2
	v_cvt_pk_bf16_f32 v3, v3, v6
	global_store_dwordx2 v[4:5], v[2:3], off offset:96
	s_branch .LBB0_128

; DI void pool_item(const bf16_t* P, bf16_t* Y, const float* pool_w, const float* pool_scale, unsigned char* lds, int cid) {
;     ...
;     __syncthreads();
; #pragma unroll
;     for (int i = 0; i < 5; ++i) {
;         const int c = tid + i * NTHR;
;         if (c < 79 * 32) {
;             const int rr = c >> 5, cc = (c & 31) * 8; const int t = t0 - 8 + rr;
;             u32x4 v = (u32x4){0u, 0u, 0u, 0u};
;             if (t >= 0 && t < T) v = *(const u32x4*)(P + (size_t)(seq0 + t) * IN_DIM + C_PU + cc);
;             *(u32x4*)(us + rr * 256 + cc) = v;
;         }
;     }
.LBB0_423:
	s_cmp_ge_i32 s34, s81
	s_mov_b64 s[18:19], -1
	s_cbranch_scc0 .LBB0_472
	s_add_i32 s2, s96, s34
	s_cmp_ge_i32 s34, s22
	s_cbranch_scc0 .LBB0_462
	s_lshl_b32 s5, s2, 6
	s_add_i32 s3, s5, 0xfffde000
	s_load_dwordx2 s[40:41], s[0:1], 0x60
	s_load_dwordx2 s[18:19], s[0:1], 0x68
	s_cmpk_lt_i32 s2, 0xa80
	s_movk_i32 s6, 0xf000
	v_mov_b32_e32 v6, v176
	s_cselect_b32 s6, s6, 0xffffff00
	s_cselect_b32 s4, 0x1000, s71
	s_and_b32 s24, s6, s3
	v_lshlrev_b32_e32 v0, 3, v6
	s_sub_i32 s6, s3, s24
	v_and_b32_e32 v10, 0xf8, v0
	s_movk_i32 s7, 0x9e0
	s_add_i32 s6, s6, -8
	v_lshl_add_u32 v8, v10, 1, 0
	v_cmp_gt_i32_e32 vcc, s7, v6
	s_waitcnt lgkmcnt(0)
	s_barrier
	s_movk_i32 s7, 0x9e0
	v_cmp_gt_i32_e32 vcc, s7, v6
	v_ashrrev_i32_e32 v57, 5, v6
	v_add_u32_e32 v0, s6, v57
	v_cmp_gt_u32_e64 s[20:21], s4, v0
	v_mov_b32_e32 v32, 0
	v_mov_b32_e32 v33, 0
	v_mov_b32_e32 v34, 0
	v_mov_b32_e32 v35, 0
	v_lshl_add_u32 v52, v57, 9, v8
	s_and_b64 s[20:21], s[20:21], vcc
	s_and_saveexec_b64 s[44:45], s[20:21]
	s_cbranch_execz .Lpool_us_skip0
	v_add_u32_e32 v0, s24, v0
	v_mov_b64_e32 v[2:3], s[76:77]
	v_mad_i64_i32 v[2:3], vcc, v0, s28, v[2:3]
	v_lshlrev_b32_e32 v0, 1, v10
	v_lshl_add_u64 v[2:3], v[2:3], 0, v[0:1]
	global_load_dwordx4 v[32:35], v[2:3], off offset:1536
.Lpool_us_skip0:
	s_or_b64 exec, exec, s[44:45]
	v_add_u32_e32 v7, 0x200, v6
	s_movk_i32 s7, 0x7e0
	v_cmp_gt_i32_e32 vcc, s7, v6
	v_ashrrev_i32_e32 v57, 5, v7
	v_add_u32_e32 v0, s6, v57
	v_cmp_gt_u32_e64 s[20:21], s4, v0
	v_mov_b32_e32 v36, 0
	v_mov_b32_e32 v37, 0
	v_mov_b32_e32 v38, 0
	v_mov_b32_e32 v39, 0
	v_lshl_add_u32 v53, v57, 9, v8
	s_and_b64 s[20:21], s[20:21], vcc
	s_and_saveexec_b64 s[44:45], s[20:21]
	s_cbranch_execz .Lpool_us_skip1
	v_add_u32_e32 v0, s24, v0
	v_mov_b64_e32 v[2:3], s[76:77]
	v_mad_i64_i32 v[2:3], vcc, v0, s28, v[2:3]
	v_lshlrev_b32_e32 v0, 1, v10
	v_lshl_add_u64 v[2:3], v[2:3], 0, v[0:1]
	global_load_dwordx4 v[36:39], v[2:3], off offset:1536
.Lpool_us_skip1:
	s_or_b64 exec, exec, s[44:45]
	v_add_u32_e32 v9, 0x400, v6
	s_movk_i32 s7, 0x5e0
	v_cmp_gt_i32_e32 vcc, s7, v6
	v_ashrrev_i32_e32 v57, 5, v9
	v_add_u32_e32 v0, s6, v57
	v_cmp_gt_u32_e64 s[20:21], s4, v0
	v_mov_b32_e32 v40, 0
	v_mov_b32_e32 v41, 0
	v_mov_b32_e32 v42, 0
	v_mov_b32_e32 v43, 0
	v_lshl_add_u32 v54, v57, 9, v8
	s_and_b64 s[20:21], s[20:21], vcc
	s_and_saveexec_b64 s[44:45], s[20:21]
	s_cbranch_execz .Lpool_us_skip2
	v_add_u32_e32 v0, s24, v0
	v_mov_b64_e32 v[2:3], s[76:77]
	v_mad_i64_i32 v[2:3], vcc, v0, s28, v[2:3]
	v_lshlrev_b32_e32 v0, 1, v10
	v_lshl_add_u64 v[2:3], v[2:3], 0, v[0:1]
	global_load_dwordx4 v[40:43], v[2:3], off offset:1536
.Lpool_us_skip2:
	s_or_b64 exec, exec, s[44:45]
	v_add_u32_e32 v11, 0x600, v6
	s_movk_i32 s7, 0x3e0
	v_cmp_gt_i32_e32 vcc, s7, v6
	v_ashrrev_i32_e32 v57, 5, v11
	v_add_u32_e32 v0, s6, v57
	v_cmp_gt_u32_e64 s[20:21], s4, v0
	v_mov_b32_e32 v44, 0
	v_mov_b32_e32 v45, 0
	v_mov_b32_e32 v46, 0
	v_mov_b32_e32 v47, 0
	v_lshl_add_u32 v55, v57, 9, v8
	s_and_b64 s[20:21], s[20:21], vcc
	s_and_saveexec_b64 s[44:45], s[20:21]
	s_cbranch_execz .Lpool_us_skip3
	v_add_u32_e32 v0, s24, v0
	v_mov_b64_e32 v[2:3], s[76:77]
	v_mad_i64_i32 v[2:3], vcc, v0, s28, v[2:3]
	v_lshlrev_b32_e32 v0, 1, v10
	v_lshl_add_u64 v[2:3], v[2:3], 0, v[0:1]
	global_load_dwordx4 v[44:47], v[2:3], off offset:1536
.Lpool_us_skip3:
	s_or_b64 exec, exec, s[44:45]
	v_add_u32_e32 v13, 0x800, v6
	s_movk_i32 s7, 0x1e0
	v_cmp_gt_i32_e32 vcc, s7, v6
	v_ashrrev_i32_e32 v57, 5, v13
	v_add_u32_e32 v0, s6, v57
	v_cmp_gt_u32_e64 s[20:21], s4, v0
	v_mov_b32_e32 v48, 0
	v_mov_b32_e32 v49, 0
	v_mov_b32_e32 v50, 0
	v_mov_b32_e32 v51, 0
	v_lshl_add_u32 v56, v57, 9, v8
	s_mov_b64 s[42:43], vcc
	s_and_b64 s[20:21], s[20:21], vcc
	s_and_saveexec_b64 s[44:45], s[20:21]
	s_cbranch_execz .Lpool_us_skip4
	v_add_u32_e32 v0, s24, v0
	v_mov_b64_e32 v[2:3], s[76:77]
	v_mad_i64_i32 v[2:3], vcc, v0, s28, v[2:3]
	v_lshlrev_b32_e32 v0, 1, v10
	v_lshl_add_u64 v[2:3], v[2:3], 0, v[0:1]
	global_load_dwordx4 v[48:51], v[2:3], off offset:1536
; DI unsigned pk_bf16(float lo, float hi) { unsigned r; asm("v_cvt_pk_bf16_f32 %0, %1, %2" : "=v"(r) : "v"(lo), "v"(hi)); return r; }
; DI void pool_item(const bf16_t* P, bf16_t* Y, const float* pool_w, const float* pool_scale, unsigned char* lds, int cid) {
;     ...
;             *(u32x4*)(us + rr * 256 + cc) = v;
;     ...
; #pragma unroll
;     for (int i = 0; i < 8; ++i) {
;         const int c = tid + i * NTHR; const int gi = c >> 4, o4 = (c & 15) * 4;
;         const f32x4 wv = *(const f32x4*)(pool_w + (size_t)gi * 64 + o4);
;         u32x2 wo; wo[0] = pk_bf16(wv[0], wv[1]); wo[1] = pk_bf16(wv[2], wv[3]);
;         *(u32x2*)(Wt + gi * 72 + o4) = wo;
;     }
;     __syncthreads();
.Lpool_us_skip4:
	s_or_b64 exec, exec, s[44:45]
	v_lshlrev_b32_e32 v12, 2, v6
	s_add_u32 s6, s40, s10
	v_and_b32_e32 v4, 60, v12
	s_addc_u32 s7, s41, s11
	v_lshlrev_b32_e32 v0, 2, v4
	v_lshl_add_u64 v[2:3], s[6:7], 0, v[0:1]
	v_lshl_add_u32 v0, v4, 1, s75
	v_mov_b32_e32 v15, 0
	v_ashrrev_i32_e32 v96, 4, v6
	v_lshlrev_b32_e32 v14, 8, v96
	v_lshl_add_u64 v[16:17], v[2:3], 0, v[14:15]
	global_load_dwordx4 v[64:67], v[16:17], off
	v_mad_u32_u24 v96, v96, s62, v0
	v_ashrrev_i32_e32 v97, 4, v7
	v_lshlrev_b32_e32 v14, 8, v97
	v_lshl_add_u64 v[16:17], v[2:3], 0, v[14:15]
	global_load_dwordx4 v[68:71], v[16:17], off
	v_mad_u32_u24 v97, v97, s62, v0
	v_ashrrev_i32_e32 v98, 4, v9
	v_lshlrev_b32_e32 v14, 8, v98
	v_lshl_add_u64 v[16:17], v[2:3], 0, v[14:15]
	global_load_dwordx4 v[72:75], v[16:17], off
	v_mad_u32_u24 v98, v98, s62, v0
	v_ashrrev_i32_e32 v99, 4, v11
	v_lshlrev_b32_e32 v14, 8, v99
	v_lshl_add_u64 v[16:17], v[2:3], 0, v[14:15]
	global_load_dwordx4 v[76:79], v[16:17], off
	v_mad_u32_u24 v99, v99, s62, v0
	v_ashrrev_i32_e32 v100, 4, v13
	v_lshlrev_b32_e32 v14, 8, v100
	v_lshl_add_u64 v[16:17], v[2:3], 0, v[14:15]
	global_load_dwordx4 v[80:83], v[16:17], off
	v_mad_u32_u24 v100, v100, s62, v0
	v_add_u32_e32 v5, 0xa00, v6
	v_ashrrev_i32_e32 v101, 4, v5
	v_lshlrev_b32_e32 v14, 8, v101
	v_lshl_add_u64 v[16:17], v[2:3], 0, v[14:15]
	global_load_dwordx4 v[84:87], v[16:17], off
	v_mad_u32_u24 v101, v101, s62, v0
	v_add_u32_e32 v5, 0xc00, v6
	v_ashrrev_i32_e32 v102, 4, v5
	v_lshlrev_b32_e32 v14, 8, v102
	v_lshl_add_u64 v[16:17], v[2:3], 0, v[14:15]
	global_load_dwordx4 v[88:91], v[16:17], off
	v_mad_u32_u24 v102, v102, s62, v0
	v_add_u32_e32 v5, 0xe00, v6
	v_ashrrev_i32_e32 v103, 4, v5
	v_lshlrev_b32_e32 v14, 8, v103
	v_lshl_add_u64 v[16:17], v[2:3], 0, v[14:15]
	global_load_dwordx4 v[92:95], v[16:17], off
	v_mad_u32_u24 v103, v103, s62, v0
	v_cmp_gt_u32_sdwa s[6:7], v6, v181 src0_sel:BYTE_0 src1_sel:DWORD
	s_waitcnt vmcnt(0)
	ds_write_b128 v52, v[32:35]
	ds_write_b128 v53, v[36:39]
	ds_write_b128 v54, v[40:43]
	ds_write_b128 v55, v[44:47]
	s_and_saveexec_b64 s[20:21], s[42:43]
	ds_write_b128 v56, v[48:51]
	s_or_b64 exec, exec, s[20:21]
	v_cvt_pk_bf16_f32 v64, v64, v65
	v_cvt_pk_bf16_f32 v65, v66, v67
	ds_write_b64 v96, v[64:65]
	v_cvt_pk_bf16_f32 v68, v68, v69
	v_cvt_pk_bf16_f32 v69, v70, v71
	ds_write_b64 v97, v[68:69]
	v_cvt_pk_bf16_f32 v72, v72, v73
	v_cvt_pk_bf16_f32 v73, v74, v75
	ds_write_b64 v98, v[72:73]
	v_cvt_pk_bf16_f32 v76, v76, v77
	v_cvt_pk_bf16_f32 v77, v78, v79
	ds_write_b64 v99, v[76:77]
	v_cvt_pk_bf16_f32 v80, v80, v81
	v_cvt_pk_bf16_f32 v81, v82, v83
	ds_write_b64 v100, v[80:81]
	v_cvt_pk_bf16_f32 v84, v84, v85
	v_cvt_pk_bf16_f32 v85, v86, v87
	ds_write_b64 v101, v[84:85]
	v_cvt_pk_bf16_f32 v88, v88, v89
	v_cvt_pk_bf16_f32 v89, v90, v91
	ds_write_b64 v102, v[88:89]
	v_cvt_pk_bf16_f32 v92, v92, v93
	v_cvt_pk_bf16_f32 v93, v94, v95
	ds_write_b64 v103, v[92:93]
	s_waitcnt lgkmcnt(0)
	s_barrier
	s_and_saveexec_b64 s[20:21], s[6:7]
	s_xor_b64 s[40:41], exec, s[20:21]
	s_cbranch_execz .LBB0_458
	v_lshrrev_b32_sdwa v0, v182, v6 dst_sel:DWORD dst_unused:UNUSED_PAD src0_sel:DWORD src1_sel:BYTE_0
	v_ashrrev_i32_e32 v4, 8, v6
	v_cmp_lt_i32_e32 vcc, 1, v0
	s_and_saveexec_b64 s[6:7], vcc
	s_xor_b64 s[42:43], exec, s[6:7]
	s_cbranch_execz .LBB0_454
	v_cmp_ne_u32_e32 vcc, 2, v0
	s_and_saveexec_b64 s[6:7], vcc
	s_xor_b64 s[44:45], exec, s[6:7]
	s_cbranch_execz .LBB0_450
	v_mul_i32_i24_e32 v0, 0x210, v4
	v_lshlrev_b32_sdwa v3, v177, v6 dst_sel:DWORD dst_unused:UNUSED_PAD src0_sel:DWORD src1_sel:BYTE_0
	v_readlane_b32 s6, v254, 45
	v_add_u32_e32 v2, s5, v4
	v_subrev_u32_e32 v2, s24, v2
	v_add3_u32 v0, v0, v3, s6
	v_lshl_or_b32 v3, v4, 9, v3
	v_add_u32_e32 v5, 0, v3
	s_mov_b32 s20, 0

; #define LAS __attribute__((address_space(3)))
; DI unsigned pk_bf16(float lo, float hi) { unsigned r; asm("v_cvt_pk_bf16_f32 %0, %1, %2" : "=v"(r) : "v"(lo), "v"(hi)); return r; }
; DI void pool_item(const bf16_t* P, bf16_t* Y, const float* pool_w, const float* pool_scale, unsigned char* lds, int cid) {
;     ...
;     {
;         const int lane = tid & 63, fr = lane & 15, fq = lane >> 4, w = tid >> 6, g = w >> 1, th = w & 1;
; #pragma unroll
;         for (int mt = 0; mt < 2; ++mt)
; #pragma unroll
;             for (int nt = 0; nt < 4; ++nt) {
;                 f32x4 acc = (f32x4){0.f, 0.f, 0.f, 0.f};
; #pragma unroll
;                 for (int ks = 0; ks < 2; ++ks) {
;                     const bf16x8 a = *(const bf16x8*)(dd + (th * 32 + mt * 16 + fr) * 264 + g * 64 + ks * 32 + fq * 8);
;                     const int wr_ = g * 64 + ks * 32 + fq * 8 + (fr >> 2), wc_ = nt * 16 + 4 * (fr & 3);
;                     const s16x4 b0 = __builtin_amdgcn_ds_read_tr16_b64_v4i16((LAS s16x4*)(Wt + wr_ * 72 + wc_)), b1 = __builtin_amdgcn_ds_read_tr16_b64_v4i16((LAS s16x4*)(Wt + (wr_ + 4) * 72 + wc_));
;                     const bf16x8 b = __builtin_shufflevector(b0, b1, 0, 1, 2, 3, 4, 5, 6, 7);
;                     acc = __builtin_amdgcn_mfma_f32_16x16x32_bf16(b, a, acc, 0, 0, 0);
;                 }
;                 const f32x4 ps = *(const f32x4*)(pool_scale + g * 64 + nt * 16 + fq * 4);
;                 u32x2 o; o[0] = pk_bf16(acc[0] * ps[0], acc[1] * ps[1]); o[1] = pk_bf16(acc[2] * ps[2], acc[3] * ps[3]);
;                 *(u32x2*)(Y + (size_t)(row0 + th * 32 + mt * 16 + fr) * 1024 + 512 + g * 64 + nt * 16 + fq * 4) = o;
.LBB0_461:
	s_or_b64 exec, exec, s[40:41]
	v_and_b32_e32 v0, 15, v6
	v_lshrrev_b32_e32 v2, 1, v6
	v_and_or_b32 v7, v2, 32, v0
	v_ashrrev_i32_e32 v0, 1, v6
	s_add_u32 s4, s18, s12
	v_bfe_u32 v5, v6, 4, 2
	v_and_b32_e32 v8, 0xffffffc0, v0
	s_addc_u32 s5, s19, s13
	v_lshlrev_b32_e32 v4, 3, v5
	v_bfe_u32 v0, v6, 2, 2
	v_ashrrev_i32_e32 v9, 31, v8
	v_or_b32_e32 v6, s3, v7
	v_lshl_add_u32 v10, v8, 1, 0
	v_or3_b32 v13, v8, v0, v4
	v_lshl_add_u64 v[2:3], v[8:9], 2, s[4:5]
	v_lshlrev_b32_e32 v0, 4, v5
	v_mul_u32_u24_e32 v5, 0x210, v7
	v_ashrrev_i32_e32 v7, 31, v6
	v_lshl_add_u64 v[2:3], v[2:3], 0, v[0:1]
	global_load_dwordx4 v[104:107], v[2:3], off
	global_load_dwordx4 v[108:111], v[2:3], off offset:64
	global_load_dwordx4 v[112:115], v[2:3], off offset:128
	global_load_dwordx4 v[116:119], v[2:3], off offset:192
	v_add3_u32 v0, v10, v0, v5
	v_lshlrev_b64 v[10:11], 11, v[6:7]
	v_lshlrev_b32_e32 v7, 1, v12
	v_mul_lo_u32 v15, v13, s62
	v_and_b32_e32 v16, 24, v7
	v_add_u32_e32 v17, s75, v15
	v_add3_u32 v7, s75, v16, v15
	v_add_u32_e32 v12, v17, v16
	s_waitcnt lgkmcnt(0)
	s_barrier
; #define LAS __attribute__((address_space(3)))
; DI unsigned pk_bf16(float lo, float hi) { unsigned r; asm("v_cvt_pk_bf16_f32 %0, %1, %2" : "=v"(r) : "v"(lo), "v"(hi)); return r; }
; DI void pool_item(const bf16_t* P, bf16_t* Y, const float* pool_w, const float* pool_scale, unsigned char* lds, int cid) {
;     ...
;         const int lane = tid & 63, fr = lane & 15, fq = lane >> 4, w = tid >> 6, g = w >> 1, th = w & 1;
; #pragma unroll
;         for (int mt = 0; mt < 2; ++mt)
; #pragma unroll
;             for (int nt = 0; nt < 4; ++nt) {
;                 f32x4 acc = (f32x4){0.f, 0.f, 0.f, 0.f};
; #pragma unroll
;                 for (int ks = 0; ks < 2; ++ks) {
;                     const bf16x8 a = *(const bf16x8*)(dd + (th * 32 + mt * 16 + fr) * 264 + g * 64 + ks * 32 + fq * 8);
;                     const int wr_ = g * 64 + ks * 32 + fq * 8 + (fr >> 2), wc_ = nt * 16 + 4 * (fr & 3);
;                     const s16x4 b0 = __builtin_amdgcn_ds_read_tr16_b64_v4i16((LAS s16x4*)(Wt + wr_ * 72 + wc_)), b1 = __builtin_amdgcn_ds_read_tr16_b64_v4i16((LAS s16x4*)(Wt + (wr_ + 4) * 72 + wc_));
;                     const bf16x8 b = __builtin_shufflevector(b0, b1, 0, 1, 2, 3, 4, 5, 6, 7);
;                     acc = __builtin_amdgcn_mfma_f32_16x16x32_bf16(b, a, acc, 0, 0, 0);
;                 }
;                 const f32x4 ps = *(const f32x4*)(pool_scale + g * 64 + nt * 16 + fq * 4);
;                 u32x2 o; o[0] = pk_bf16(acc[0] * ps[0], acc[1] * ps[1]); o[1] = pk_bf16(acc[2] * ps[2], acc[3] * ps[3]);
;                 *(u32x2*)(Y + (size_t)(row0 + th * 32 + mt * 16 + fr) * 1024 + 512 + g * 64 + nt * 16 + fq * 4) = o;
;             }
	ds_read_b128 v[18:21], v0 offset:40512
	ds_read_b64_tr_b16 v[22:23], v7
	ds_read_b64_tr_b16 v[24:25], v12 offset:576
	s_waitcnt lgkmcnt(0)
	v_mfma_f32_16x16x32_bf16 v[18:21], v[22:25], v[18:21], 0
	ds_read_b128 v[22:25], v0 offset:40576
	ds_read_b64_tr_b16 v[26:27], v7 offset:4608
	ds_read_b64_tr_b16 v[28:29], v7 offset:5184
	v_readlane_b32 s4, v254, 53
	v_readlane_b32 s5, v254, 54
	s_waitcnt lgkmcnt(0)
	v_mfma_f32_16x16x32_bf16 v[18:21], v[26:29], v[22:25], v[18:21]
	s_nop 0
	v_lshl_add_u64 v[10:11], s[4:5], 0, v[10:11]
	v_lshlrev_b64 v[8:9], 1, v[8:9]
	v_lshl_add_u64 v[10:11], v[10:11], 0, v[8:9]
	v_mov_b32_e32 v5, v1
	v_lshl_add_u64 v[10:11], v[10:11], 0, v[4:5]
	s_mov_b64 s[18:19], 0
	s_waitcnt vmcnt(0)
	v_mul_f32_e32 v14, v19, v105
	v_mul_f32_e32 v13, v18, v104
	v_cvt_pk_bf16_f32 v18, v13, v14
	v_mul_f32_e32 v14, v21, v107
	v_mul_f32_e32 v13, v20, v106
	v_cvt_pk_bf16_f32 v19, v13, v14
	v_or_b32_e32 v14, 32, v16
	global_store_dwordx2 v[10:11], v[18:19], off offset:1024
	v_add_u32_e32 v13, v17, v14
	ds_read_b128 v[18:21], v0 offset:40512
	ds_read_b64_tr_b16 v[22:23], v13
	ds_read_b64_tr_b16 v[24:25], v12 offset:608
	v_add3_u32 v14, s75, v14, v15
	s_waitcnt lgkmcnt(0)
	v_mfma_f32_16x16x32_bf16 v[18:21], v[22:25], v[18:21], 0
	ds_read_b128 v[22:25], v0 offset:40576
	ds_read_b64_tr_b16 v[26:27], v14 offset:4608
	ds_read_b64_tr_b16 v[28:29], v7 offset:5216
	s_waitcnt lgkmcnt(0)
	v_mfma_f32_16x16x32_bf16 v[18:21], v[26:29], v[22:25], v[18:21]
	s_nop 0
	v_or_b32_e32 v26, 64, v16
	v_add_u32_e32 v30, v17, v26
	v_add3_u32 v31, s75, v26, v15
	s_nop 0
	s_nop 2
	v_mul_f32_e32 v18, v18, v108
	v_mul_f32_e32 v19, v19, v109
	v_cvt_pk_bf16_f32 v18, v18, v19
	v_mul_f32_e32 v19, v20, v110
	v_mul_f32_e32 v20, v21, v111
	v_cvt_pk_bf16_f32 v19, v19, v20
	global_store_dwordx2 v[10:11], v[18:19], off offset:1056
	ds_read_b128 v[18:21], v0 offset:40512
	ds_read_b64_tr_b16 v[22:23], v30
	ds_read_b64_tr_b16 v[24:25], v12 offset:640
	s_waitcnt lgkmcnt(0)
	v_mfma_f32_16x16x32_bf16 v[18:21], v[22:25], v[18:21], 0
	ds_read_b128 v[22:25], v0 offset:40576
	ds_read_b64_tr_b16 v[26:27], v31 offset:4608
	ds_read_b64_tr_b16 v[28:29], v7 offset:5248
	s_waitcnt lgkmcnt(0)
	v_mfma_f32_16x16x32_bf16 v[18:21], v[26:29], v[22:25], v[18:21]
	s_nop 0
	v_or_b32_e32 v26, 0x60, v16
	v_add_u32_e32 v28, v17, v26
	v_add3_u32 v29, s75, v26, v15
	s_nop 0
	s_nop 2
	v_mul_f32_e32 v18, v18, v112
	v_mul_f32_e32 v19, v19, v113
	v_cvt_pk_bf16_f32 v18, v18, v19
	v_mul_f32_e32 v19, v20, v114
	v_mul_f32_e32 v20, v21, v115
	v_cvt_pk_bf16_f32 v19, v19, v20
	global_store_dwordx2 v[10:11], v[18:19], off offset:1088
	ds_read_b128 v[18:21], v0 offset:40512
	ds_read_b64_tr_b16 v[22:23], v28
	ds_read_b64_tr_b16 v[24:25], v12 offset:672
	s_waitcnt lgkmcnt(0)
	v_mfma_f32_16x16x32_bf16 v[16:19], v[22:25], v[18:21], 0
	ds_read_b128 v[20:23], v0 offset:40576
	ds_read_b64_tr_b16 v[24:25], v29 offset:4608
	ds_read_b64_tr_b16 v[26:27], v7 offset:5280
	s_waitcnt lgkmcnt(0)
	v_mfma_f32_16x16x32_bf16 v[16:19], v[24:27], v[20:23], v[16:19]
	s_nop 0
	s_nop 0
	s_nop 5
	v_mul_f32_e32 v15, v16, v116
	v_mul_f32_e32 v16, v17, v117
	v_mul_f32_e32 v17, v19, v119
	v_cvt_pk_bf16_f32 v16, v15, v16
	v_mul_f32_e32 v15, v18, v118
	v_cvt_pk_bf16_f32 v17, v15, v17
	global_store_dwordx2 v[10:11], v[16:17], off offset:1120
	v_or_b32_e32 v10, 16, v6
	v_ashrrev_i32_e32 v11, 31, v10
	v_lshlrev_b64 v[10:11], 11, v[10:11]
	v_lshl_add_u64 v[10:11], s[4:5], 0, v[10:11]
	v_lshl_add_u64 v[8:9], v[10:11], 0, v[8:9]
	v_lshl_add_u64 v[4:5], v[8:9], 0, v[4:5]
	ds_read_b128 v[8:11], v0 offset:48960
	ds_read_b64_tr_b16 v[16:17], v7
	ds_read_b64_tr_b16 v[18:19], v12 offset:576
	s_waitcnt lgkmcnt(0)
	v_mfma_f32_16x16x32_bf16 v[8:11], v[16:19], v[8:11], 0
	ds_read_b128 v[16:19], v0 offset:49024
	ds_read_b64_tr_b16 v[20:21], v7 offset:4608
	ds_read_b64_tr_b16 v[22:23], v7 offset:5184
	s_waitcnt lgkmcnt(0)
	v_mfma_f32_16x16x32_bf16 v[8:11], v[20:23], v[16:19], v[8:11]
	s_nop 0
	s_nop 0
	s_nop 5
	v_mul_f32_e32 v6, v8, v104
	v_mul_f32_e32 v8, v9, v105
	v_mul_f32_e32 v9, v11, v107
	v_cvt_pk_bf16_f32 v8, v6, v8
	v_mul_f32_e32 v6, v10, v106
	v_cvt_pk_bf16_f32 v9, v6, v9
	global_store_dwordx2 v[4:5], v[8:9], off offset:1024
	ds_read_b128 v[8:11], v0 offset:48960
	ds_read_b64_tr_b16 v[16:17], v13
	ds_read_b64_tr_b16 v[18:19], v12 offset:608
	s_waitcnt lgkmcnt(0)
	v_mfma_f32_16x16x32_bf16 v[8:11], v[16:19], v[8:11], 0
	ds_read_b128 v[16:19], v0 offset:49024
	ds_read_b64_tr_b16 v[20:21], v14 offset:4608
	ds_read_b64_tr_b16 v[22:23], v7 offset:5216
	s_waitcnt lgkmcnt(0)
	v_mfma_f32_16x16x32_bf16 v[8:11], v[20:23], v[16:19], v[8:11]
	s_nop 0
	s_nop 0
	s_nop 5
	v_mul_f32_e32 v6, v8, v108
	v_mul_f32_e32 v8, v9, v109
	v_mul_f32_e32 v9, v11, v111
	v_cvt_pk_bf16_f32 v8, v6, v8
	v_mul_f32_e32 v6, v10, v110
	v_cvt_pk_bf16_f32 v9, v6, v9
	global_store_dwordx2 v[4:5], v[8:9], off offset:1056
	ds_read_b128 v[8:11], v0 offset:48960
	ds_read_b64_tr_b16 v[14:15], v30
	ds_read_b64_tr_b16 v[16:17], v12 offset:640
	s_waitcnt lgkmcnt(0)
	v_mfma_f32_16x16x32_bf16 v[8:11], v[14:17], v[8:11], 0
	ds_read_b128 v[14:17], v0 offset:49024
	ds_read_b64_tr_b16 v[18:19], v31 offset:4608
	ds_read_b64_tr_b16 v[20:21], v7 offset:5248
	s_waitcnt lgkmcnt(0)
	v_mfma_f32_16x16x32_bf16 v[8:11], v[18:21], v[14:17], v[8:11]
	s_nop 0
	s_nop 0
	s_nop 5
	v_mul_f32_e32 v6, v8, v112
	v_mul_f32_e32 v8, v9, v113
	v_mul_f32_e32 v9, v11, v115
	v_cvt_pk_bf16_f32 v8, v6, v8
	v_mul_f32_e32 v6, v10, v114
	v_cvt_pk_bf16_f32 v9, v6, v9
	global_store_dwordx2 v[4:5], v[8:9], off offset:1088
	ds_read_b128 v[8:11], v0 offset:48960
	ds_read_b64_tr_b16 v[14:15], v28
	ds_read_b64_tr_b16 v[16:17], v12 offset:672
	s_waitcnt lgkmcnt(0)
	v_mfma_f32_16x16x32_bf16 v[8:11], v[14:17], v[8:11], 0
	ds_read_b128 v[12:15], v0 offset:49024
	ds_read_b64_tr_b16 v[16:17], v29 offset:4608
	ds_read_b64_tr_b16 v[18:19], v7 offset:5280
	s_waitcnt lgkmcnt(0)
	v_mfma_f32_16x16x32_bf16 v[6:9], v[16:19], v[12:15], v[8:11]
	s_nop 2
	s_nop 0
	s_nop 0
	s_nop 2
	v_mul_f32_e32 v0, v6, v116
	v_mul_f32_e32 v2, v7, v117
	v_mul_f32_e32 v3, v9, v119
	v_cvt_pk_bf16_f32 v2, v0, v2
	v_mul_f32_e32 v0, v8, v118
	v_cvt_pk_bf16_f32 v3, v0, v3
	global_store_dwordx2 v[4:5], v[2:3], off offset:1120
